# in-proj rows[0,HALF0) tile hand-off: the 32 workgroups with a third down-projection tile give their last 2 in-projection tiles to workgroups that had six
# speedup vs baseline: 1.0084x; 1.0084x over previous
;     __host__ __device__ bool next(int i, Unit& u) const {
;         const long L = (long)i * G + c; if (L >= nwg) return false;
;         int wgid = (int)L; { const int q = nwg / NXCD, r = nwg % NXCD, xcd = wgid % NXCD, off = wgid / NXCD; wgid = (xcd < r ? xcd * (q + 1) : r * (q + 1) + (xcd - r) * q) + off; }
;         const int nig = WGM * nN, gid = wgid / nig, fm = gid * WGM, gsz = (nM - fm) < WGM ? (nM - fm) : WGM;
;         u.pm = fm + ((wgid % nig) % gsz); u.pn = (wgid % nig) / gsz; return true;
.LBB0_1272:
	s_add_i32 s56, s56, 1
	s_mul_i32 s10, s56, s31
	s_mul_hi_u32 s11, s56, s70
	s_add_i32 s11, s11, s10
	s_mul_i32 s10, s56, s70
	s_add_u32 s34, s10, s73
	s_addc_u32 s35, s11, s77
	s_cmp_lt_u32 s73, 224
	s_cbranch_scc1 .Lrb6_a
	s_cmp_lt_u32 s56, 4
	s_cbranch_scc1 .Lrb6_done
	s_mov_b32 s34, 0x7fffffff
	s_mov_b32 s35, 0
	s_branch .Lrb6_done
.Lrb6_a:
	s_cmp_lt_u32 s73, 128
	s_cbranch_scc1 .Lrb6_done
	s_cmp_ge_u32 s73, 192
	s_cbranch_scc1 .Lrb6_done
	s_cmp_lg_u32 s56, 6
	s_cbranch_scc1 .Lrb6_done
	s_sub_i32 s10, s73, 128
	s_lshr_b32 s11, s10, 5
	s_and_b32 s10, s10, 31
	s_add_i32 s11, s11, 4
	s_lshl_b32 s11, s11, 8
	s_add_i32 s34, s11, s10
	s_addk_i32 s34, 0xe0
	s_mov_b32 s35, 0
.Lrb6_done:
	v_cmp_gt_i64_e32 vcc, s[34:35], v[174:175]
	v_cmp_lt_i64_e64 s[38:39], s[34:35], v[172:173]
	s_cbranch_vccnz .LBB0_1274
	s_ashr_i32 s10, s34, 31
	s_lshr_b32 s10, s10, 29
	s_add_i32 s10, s34, s10
	s_ashr_i32 s11, s10, 3
	s_and_b32 s10, s10, -8
	s_sub_i32 s10, s34, s10
	s_cmp_lt_i32 s10, 0
	s_cselect_b32 s26, s66, 0xd0
	s_mul_i32 s10, s10, s26
	s_add_i32 s10, s10, s11
	s_mul_hi_i32 s11, s10, 0x4ec4ec4f
	s_lshr_b32 s26, s11, 31
	s_ashr_i32 s11, s11, 5
	s_add_i32 s11, s11, s26
	s_lshl_b32 s27, s11, 3
	s_sub_i32 s26, 0x80, s27
	s_min_i32 s34, s26, 8
	s_abs_i32 s26, s34
	v_cvt_f32_u32_e32 v2, s26
	s_sub_i32 s42, 0, s26
	s_mulk_i32 s11, 0x68
	s_sub_i32 s10, s10, s11
	v_rcp_iflag_f32_e32 v2, v2
	s_abs_i32 s11, s10
	s_xor_b32 s35, s10, s34
	s_ashr_i32 s35, s35, 31
	v_mul_f32_e32 v2, 0x4f7ffffe, v2
	v_cvt_u32_f32_e32 v2, v2
	s_nop 0
	v_readfirstlane_b32 s43, v2
	s_mul_i32 s42, s42, s43
	s_mul_hi_u32 s42, s43, s42
	s_add_i32 s43, s43, s42
	s_mul_hi_u32 s42, s11, s43
	s_mul_i32 s43, s42, s26
	s_sub_i32 s11, s11, s43
	s_add_i32 s44, s42, 1
	s_sub_i32 s43, s11, s26
	s_cmp_ge_u32 s11, s26
	s_cselect_b32 s42, s44, s42
	s_cselect_b32 s11, s43, s11
	s_add_i32 s43, s42, 1
	s_cmp_ge_u32 s11, s26
	s_cselect_b32 s11, s43, s42
	s_xor_b32 s11, s11, s35
	s_sub_i32 s26, s11, s35
	s_mul_i32 s11, s26, s34
	s_sub_i32 s10, s10, s11
	s_add_i32 s42, s27, s10
